# one static s_setprio 1 at kernel entry for workgroups with blockIdx < 256 (the more heavily loaded workgroup of each CU pair)
# baseline (speedup 1.0000x reference)
.LBB0_15:
	s_or_b64 exec, exec, s[0:1]
	v_readlane_b32 s0, v247, 0
	s_nop 1
	s_cmp_ge_u32 s0, 0x100
	s_cbranch_scc1 .Lprio_skip
	s_setprio 1
.Lprio_skip:
	v_mov_b32_e32 v0, v187
	s_cmp_eq_u32 s0, 0
	s_movk_i32 s2, 0x400
	s_cselect_b64 s[0:1], -1, 0
	v_cmp_gt_i32_e32 vcc, s2, v0
	s_and_b64 s[2:3], s[0:1], vcc
	s_and_saveexec_b64 s[0:1], s[2:3]
	s_cbranch_execz .LBB0_26
	v_and_b32_e32 v1, 15, v0
	v_cvt_f64_u32_e32 v[2:3], v1
	v_ldexp_f64 v[4:5], v[2:3], -4
	v_mov_b32_e32 v1, 0x40c38800
	v_mov_b32_e32 v2, 0x3ff00000
	v_cmp_eq_f64_e32 vcc, 0, v[4:5]
	v_mov_b32_e32 v3, 0
	v_mov_b32_e32 v6, v3
	v_cndmask_b32_e32 v7, v1, v2, vcc
	v_frexp_exp_i32_f64_e32 v1, v[6:7]
	v_frexp_mant_f64_e32 v[6:7], v[6:7]
	s_mov_b32 s3, 0x3fe55555
	s_mov_b32 s2, 0x55555555
	v_cmp_gt_f64_e32 vcc, s[2:3], v[6:7]
	s_mov_b32 s6, 0x4222de17
	s_mov_b32 s7, 0x3fbdee67
	v_cndmask_b32_e64 v2, 0, 1, vcc
	v_ldexp_f64 v[6:7], v[6:7], v2
	v_add_f64 v[8:9], v[6:7], 1.0
	v_rcp_f64_e32 v[10:11], v[8:9]
	v_add_f64 v[14:15], v[8:9], -1.0
	v_add_f64 v[12:13], v[6:7], -1.0
	v_add_f64 v[6:7], v[6:7], -v[14:15]
	v_fma_f64 v[14:15], -v[8:9], v[10:11], 1.0
	v_fmac_f64_e32 v[10:11], v[14:15], v[10:11]
	v_fma_f64 v[14:15], -v[8:9], v[10:11], 1.0
	v_fmac_f64_e32 v[10:11], v[14:15], v[10:11]
	v_mul_f64 v[14:15], v[12:13], v[10:11]
	v_mul_f64 v[16:17], v[8:9], v[14:15]
	v_fma_f64 v[8:9], v[14:15], v[8:9], -v[16:17]
	v_fmac_f64_e32 v[8:9], v[14:15], v[6:7]
	v_add_f64 v[6:7], v[16:17], v[8:9]
	v_add_f64 v[18:19], v[12:13], -v[6:7]
	v_add_f64 v[16:17], v[6:7], -v[16:17]
	v_add_f64 v[12:13], v[12:13], -v[18:19]
	v_add_f64 v[6:7], v[12:13], -v[6:7]
	v_add_f64 v[8:9], v[16:17], -v[8:9]
	v_add_f64 v[6:7], v[8:9], v[6:7]
	v_add_f64 v[6:7], v[18:19], v[6:7]
	v_mul_f64 v[6:7], v[10:11], v[6:7]
	v_add_f64 v[8:9], v[14:15], v[6:7]
	v_add_f64 v[10:11], v[8:9], -v[14:15]
	v_add_f64 v[6:7], v[6:7], -v[10:11]
	v_mul_f64 v[10:11], v[8:9], v[8:9]
	v_fma_f64 v[12:13], v[8:9], v[8:9], -v[10:11]
	v_add_f64 v[14:15], v[6:7], v[6:7]
	v_fmac_f64_e32 v[12:13], v[8:9], v[14:15]
	v_add_f64 v[14:15], v[10:11], v[12:13]
	v_add_f64 v[10:11], v[14:15], -v[10:11]
	v_add_f64 v[10:11], v[12:13], -v[10:11]
	v_mov_b32_e32 v12, 0x968915a9
	v_mov_b32_e32 v13, 0x3fba6564
	v_fmac_f64_e32 v[12:13], s[6:7], v[14:15]
	v_mov_b32_e32 v16, 0x3abe935a
	v_mov_b32_e32 v17, 0x3fbe25e4
	v_fmac_f64_e32 v[16:17], v[14:15], v[12:13]
	v_mov_b32_e32 v12, 0x47e6c9c2
	v_mov_b32_e32 v13, 0x3fc110ef
	v_fmac_f64_e32 v[12:13], v[14:15], v[16:17]
	v_mov_b32_e32 v16, 0xcfa74449
	v_mov_b32_e32 v17, 0x3fc3b13b
	v_fmac_f64_e32 v[16:17], v[14:15], v[12:13]
	v_mov_b32_e32 v12, 0x71bf3c30
	v_mov_b32_e32 v13, 0x3fc745d1
	v_fmac_f64_e32 v[12:13], v[14:15], v[16:17]
	v_mov_b32_e32 v16, 0x1c7792ce
	v_mov_b32_e32 v17, 0x3fcc71c7
	v_fmac_f64_e32 v[16:17], v[14:15], v[12:13]
	v_mov_b32_e32 v12, 0x924920da
	v_mov_b32_e32 v13, 0x3fd24924
	v_subbrev_co_u32_e32 v1, vcc, 0, v1, vcc
	v_fmac_f64_e32 v[12:13], v[14:15], v[16:17]
	v_mov_b32_e32 v16, 0x9999999c
	v_mov_b32_e32 v17, 0x3fd99999
	v_fmac_f64_e32 v[16:17], v[14:15], v[12:13]
	v_cvt_f64_i32_e32 v[12:13], v1
	s_mov_b32 s7, 0x3fe62e42
	s_mov_b32 s6, 0xfefa39ef
	v_mul_f64 v[18:19], v[12:13], s[6:7]
	v_mul_f64 v[24:25], v[8:9], v[14:15]
	v_fma_f64 v[20:21], v[12:13], s[6:7], -v[18:19]
	s_mov_b32 s11, 0x3c7abc9e
	s_mov_b32 s10, 0x3b39803f
	v_fma_f64 v[26:27], v[14:15], v[8:9], -v[24:25]
	v_fmac_f64_e32 v[20:21], s[10:11], v[12:13]
	v_fmac_f64_e32 v[26:27], v[14:15], v[6:7]
	v_add_f64 v[12:13], v[18:19], v[20:21]
	v_fmac_f64_e32 v[26:27], v[10:11], v[8:9]
	v_add_f64 v[18:19], v[12:13], -v[18:19]
	v_ldexp_f64 v[22:23], v[6:7], 1
	v_add_f64 v[6:7], v[24:25], v[26:27]
	v_add_f64 v[18:19], v[20:21], -v[18:19]
	v_ldexp_f64 v[20:21], v[8:9], 1
	v_add_f64 v[8:9], v[6:7], -v[24:25]
	v_mul_f64 v[24:25], v[14:15], v[16:17]
	v_fma_f64 v[14:15], v[14:15], v[16:17], -v[24:25]
	v_fmac_f64_e32 v[14:15], v[10:11], v[16:17]
	v_add_f64 v[10:11], v[24:25], v[14:15]
	v_add_f64 v[16:17], v[10:11], -v[24:25]
	v_add_f64 v[14:15], v[14:15], -v[16:17]
	v_add_f64 v[16:17], v[10:11], s[2:3]
	s_mov_b32 s3, 0xbfe55555
	v_add_f64 v[24:25], v[16:17], s[2:3]
	s_mov_b32 s2, 0xd5df274d
	s_mov_b32 s3, 0x3c8543b0
	v_add_f64 v[10:11], v[10:11], -v[24:25]
	v_add_f64 v[14:15], v[14:15], s[2:3]
	v_add_f64 v[10:11], v[14:15], v[10:11]
	v_add_f64 v[14:15], v[16:17], v[10:11]
	v_add_f64 v[16:17], v[16:17], -v[14:15]
	v_add_f64 v[10:11], v[10:11], v[16:17]
	v_mul_f64 v[16:17], v[6:7], v[14:15]
	v_fma_f64 v[24:25], v[6:7], v[14:15], -v[16:17]
	v_add_f64 v[8:9], v[26:27], -v[8:9]
	v_fmac_f64_e32 v[24:25], v[6:7], v[10:11]
	v_fmac_f64_e32 v[24:25], v[8:9], v[14:15]
	v_add_f64 v[6:7], v[16:17], v[24:25]
	v_add_f64 v[8:9], v[6:7], -v[16:17]
	v_add_f64 v[10:11], v[20:21], v[6:7]
	v_add_f64 v[8:9], v[24:25], -v[8:9]
	v_add_f64 v[14:15], v[10:11], -v[20:21]
	v_add_f64 v[6:7], v[6:7], -v[14:15]
	v_add_f64 v[8:9], v[22:23], v[8:9]
	v_add_f64 v[6:7], v[8:9], v[6:7]
	v_add_f64 v[8:9], v[10:11], v[6:7]
	v_add_f64 v[10:11], v[8:9], -v[10:11]
	v_add_f64 v[6:7], v[6:7], -v[10:11]
	v_add_f64 v[10:11], v[12:13], v[8:9]
	v_add_f64 v[14:15], v[10:11], -v[12:13]
	v_add_f64 v[16:17], v[10:11], -v[14:15]
	v_add_f64 v[12:13], v[12:13], -v[16:17]
	v_add_f64 v[8:9], v[8:9], -v[14:15]
	v_add_f64 v[8:9], v[8:9], v[12:13]
	v_add_f64 v[12:13], v[18:19], v[6:7]
	v_add_f64 v[14:15], v[12:13], -v[18:19]
	v_add_f64 v[8:9], v[12:13], v[8:9]
	v_add_f64 v[16:17], v[12:13], -v[14:15]
	v_add_f64 v[12:13], v[10:11], v[8:9]
	v_add_f64 v[16:17], v[18:19], -v[16:17]
	v_add_f64 v[6:7], v[6:7], -v[14:15]
	v_add_f64 v[10:11], v[12:13], -v[10:11]
	v_add_f64 v[6:7], v[6:7], v[16:17]
	v_add_f64 v[8:9], v[8:9], -v[10:11]
	v_add_f64 v[6:7], v[6:7], v[8:9]
	v_add_f64 v[8:9], v[12:13], v[6:7]
	v_add_f64 v[10:11], v[8:9], -v[12:13]
	v_add_f64 v[6:7], v[6:7], -v[10:11]
	v_mul_f64 v[10:11], v[4:5], v[8:9]
	v_fma_f64 v[8:9], v[4:5], v[8:9], -v[10:11]
	v_fmac_f64_e32 v[8:9], v[4:5], v[6:7]
	s_movk_i32 s12, 0x204
	v_add_f64 v[6:7], v[10:11], v[8:9]
	v_cmp_class_f64_e64 vcc, v[10:11], s12
	s_mov_b32 s2, 0x652b82fe
	v_add_f64 v[12:13], v[6:7], -v[10:11]
	v_cndmask_b32_e32 v7, v7, v11, vcc
	v_cndmask_b32_e32 v6, v6, v10, vcc
	s_mov_b32 s3, 0x3ff71547
	v_mul_f64 v[10:11], v[6:7], s[2:3]
	v_rndne_f64_e32 v[10:11], v[10:11]
	s_mov_b32 s7, 0xbfe62e42
	v_add_f64 v[8:9], v[8:9], -v[12:13]
	v_fma_f64 v[12:13], s[6:7], v[10:11], v[6:7]
	s_mov_b32 s11, 0xbc7abc9e
	s_mov_b32 s2, 0x6a5dcb37
	v_fmac_f64_e32 v[12:13], s[10:11], v[10:11]
	v_mov_b32_e32 v14, 0xfca7ab0c
	v_mov_b32_e32 v15, 0x3e928af3
	s_mov_b32 s3, 0x3e5ade15
	v_fmac_f64_e32 v[14:15], s[2:3], v[12:13]
	v_mov_b32_e32 v16, 0x623fde64
	v_mov_b32_e32 v17, 0x3ec71dee
	v_fmac_f64_e32 v[16:17], v[12:13], v[14:15]
	v_mov_b32_e32 v14, 0x7c89e6b0
	v_mov_b32_e32 v15, 0x3efa0199
	v_fmac_f64_e32 v[14:15], v[12:13], v[16:17]
	v_mov_b32_e32 v16, 0x14761f6e
	v_mov_b32_e32 v17, 0x3f2a01a0
	v_fmac_f64_e32 v[16:17], v[12:13], v[14:15]
	v_mov_b32_e32 v14, 0x1852b7b0
	v_mov_b32_e32 v15, 0x3f56c16c
	v_fmac_f64_e32 v[14:15], v[12:13], v[16:17]
	v_mov_b32_e32 v16, 0x11122322
	v_mov_b32_e32 v17, 0x3f811111
	v_fmac_f64_e32 v[16:17], v[12:13], v[14:15]
	v_mov_b32_e32 v14, 0x555502a1
	v_mov_b32_e32 v15, 0x3fa55555
	s_mov_b32 s8, 0
	v_fmac_f64_e32 v[14:15], v[12:13], v[16:17]
	v_mov_b32_e32 v16, 0x55555511
	v_mov_b32_e32 v17, 0x3fc55555
	s_mov_b32 s9, 0x7ff00000
	v_fmac_f64_e32 v[16:17], v[12:13], v[14:15]
	v_mov_b32_e32 v14, 11
	v_mov_b32_e32 v15, 0x3fe00000
	s_mov_b32 s2, 0
	v_cmp_neq_f64_e64 vcc, |v[6:7]|, s[8:9]
	v_fmac_f64_e32 v[14:15], v[12:13], v[16:17]
	s_mov_b32 s3, 0x40900000
	v_cndmask_b32_e32 v9, 0, v9, vcc
	v_cndmask_b32_e32 v8, 0, v8, vcc
	v_fma_f64 v[14:15], v[12:13], v[14:15], 1.0
	v_cmp_nlt_f64_e32 vcc, s[2:3], v[6:7]
	s_mov_b32 s2, 0
	v_fma_f64 v[12:13], v[12:13], v[14:15], 1.0
	v_cvt_i32_f64_e32 v1, v[10:11]
	s_mov_b32 s3, 0xc090cc00
	v_ldexp_f64 v[10:11], v[12:13], v1
	v_mov_b32_e32 v1, 0x7ff00000
	v_cmp_ngt_f64_e64 s[6:7], s[2:3], v[6:7]
	v_cndmask_b32_e32 v1, v1, v11, vcc
	s_and_b64 vcc, s[6:7], vcc
	v_cndmask_b32_e64 v7, 0, v1, s[6:7]
	v_cndmask_b32_e32 v6, 0, v10, vcc
	v_mov_b64_e32 v[10:11], v[6:7]
	v_fmac_f64_e32 v[10:11], v[10:11], v[8:9]
	v_cmp_class_f64_e64 vcc, v[6:7], s12
	v_readlane_b32 s36, v247, 49
	v_ashrrev_i32_e32 v1, 31, v0
	v_cndmask_b32_e32 v7, v11, v7, vcc
	v_cndmask_b32_e32 v6, v10, v6, vcc
	v_and_b32_e32 v9, 0x7fffffff, v7
	v_mov_b32_e32 v8, v6
	v_div_scale_f64 v[10:11], s[2:3], v[8:9], v[8:9], 1.0
	v_rcp_f64_e32 v[12:13], v[10:11]
	v_div_scale_f64 v[8:9], vcc, 1.0, v[8:9], 1.0
	v_readlane_b32 s40, v247, 53
	v_fma_f64 v[14:15], -v[10:11], v[12:13], 1.0
	v_fmac_f64_e32 v[12:13], v[12:13], v[14:15]
	v_fma_f64 v[14:15], -v[10:11], v[12:13], 1.0
	v_fmac_f64_e32 v[12:13], v[12:13], v[14:15]
	v_mul_f64 v[14:15], v[8:9], v[12:13]
	v_fma_f64 v[8:9], -v[10:11], v[14:15], v[8:9]
	v_div_fmas_f64 v[8:9], v[8:9], v[12:13], v[14:15]
	v_div_fixup_f64 v[6:7], v[8:9], |v[6:7]|, 1.0
	v_cmp_neq_f64_e32 vcc, s[8:9], v[4:5]
	v_readlane_b32 s41, v247, 54
	v_readlane_b32 s37, v247, 50
	v_cndmask_b32_e32 v5, 0, v7, vcc
	v_cndmask_b32_e32 v4, 0, v6, vcc
	v_readlane_b32 s38, v247, 51
	v_readlane_b32 s39, v247, 52
	v_readlane_b32 s42, v247, 55
	v_lshl_add_u64 v[6:7], v[0:1], 2, s[40:41]
	s_mov_b64 s[6:7], 0x1000
	s_mov_b64 s[2:3], 0
	v_lshl_add_u64 v[6:7], v[6:7], 0, s[6:7]
	s_mov_b32 s34, 0xfe5163ab
	s_mov_b32 s35, 0x3c439041
	s_mov_b32 s36, 0xdb629599
	s_mov_b32 s37, 0xf534ddc0
	s_mov_b32 s38, 0xfc2757d1
	s_mov_b32 s39, 0x4e441529
	s_mov_b32 s40, 0xa2f9836e
	s_mov_b32 s41, 0x3fc90fda
	s_mov_b32 s42, 0xbfc90fda
	v_mov_b32_e32 v1, 0x3c0881c4
	v_mov_b32_e32 v8, 0xbab64f3b
	v_not_b32_e32 v9, 63
	v_not_b32_e32 v10, 31
	v_mov_b32_e32 v11, 0x7fc00000
	v_mov_b32_e32 v12, v0
	v_readlane_b32 s43, v247, 56
	v_readlane_b32 s44, v247, 57
	v_readlane_b32 s45, v247, 58
	v_readlane_b32 s46, v247, 59
	v_readlane_b32 s47, v247, 60
	v_readlane_b32 s48, v247, 61
	v_readlane_b32 s49, v247, 62
	v_readlane_b32 s50, v247, 63
	v_readlane_b32 s51, v246, 0
	s_branch .LBB0_18
